# A3 merge epilogue: 128 two-byte loads grouped 4 rows at a time and pipelined (was 64 serialized round trips per unit) + MLA rotary table preloaded as 8 dwordx4 (was 16 serialized loads per unit); iden
# speedup vs baseline: 1.0473x; 1.0105x over previous
; __device__ __forceinline__ unsigned cvt_pk_bf16(float lo, float hi) { unsigned r; asm volatile("v_cvt_pk_bf16_f32 %0, %1, %2" : "=v"(r) : "v"(lo), "v"(hi)); return r; }
; __device__ __forceinline__ float bf2f(unsigned short h) { return __uint_as_float(((unsigned)h) << 16); }
; template <int MODE>
; __device__ __forceinline__ void body(const Desc& d, char* lds, int wave_id) {
;     ...
;   { const bf16_t* Qw = d.Q + (size_t)qtok * d.ldq + hi * 8;
; #pragma unroll
;     for (int d0 = 0; d0 < NQ; ++d0) qr[d0] = *reinterpret_cast<const bf16x8*>(Qw + d0 * 16);
;     if constexpr (MODE == 1) {
;       const f32x2* rp = d.rope + (size_t)(d.pos0 + vq) * 32 + hi * 8;
; #pragma unroll
;       for (int dd = 0; dd < 2; ++dd) { bf16x8 x1 = qr[8 + dd], x2 = qr[10 + dd]; bf16x8 y1, y2;
; #pragma unroll
;         for (int e = 0; e < 8; ++e) { const f32x2 cs = rp[dd * 16 + e]; const float a = bf2f((unsigned short)x1[e]), b = bf2f((unsigned short)x2[e]);
;           const float o1 = a * cs.x - b * cs.y, o2 = b * cs.x + a * cs.y; const unsigned pk = cvt_pk_bf16(o1, o2); y1[e] = (short)(pk & 0xffff); y2[e] = (short)(pk >> 16); }
;         qr[8 + dd] = y1; qr[10 + dd] = y2; }
.LBB0_796:
	s_lshl_b32 s38, s46, 11
	s_add_i32 s44, s38, 0x6000
	s_mul_i32 s38, s69, 0xc0
	s_ashr_i32 s39, s38, 31
	s_lshl_b32 s45, s46, 13
	s_lshl_b64 s[38:39], s[38:39], 1
	s_add_u32 s38, s55, s38
	s_addc_u32 s39, s64, s39
	s_lshl_b32 s40, s69, 8
	s_ashr_i32 s41, s40, 31
	s_lshl_b64 s[40:41], s[40:41], 1
	s_add_u32 s60, s65, s40
	s_addc_u32 s61, s66, s41
	s_lshl_b32 s40, s47, 8
	s_cmp_lt_i32 s46, 4
	s_waitcnt vmcnt(0)
	s_barrier
	v_mbcnt_lo_u32_b32 v0, -1, 0
	v_mbcnt_hi_u32_b32 v0, -1, v0
	s_cselect_b32 s44, s45, s44
	v_add_u32_e32 v48, s29, v0
	s_cselect_b32 s70, 0x80, 32
	v_ashrrev_i32_e32 v0, 6, v48
	v_and_b32_e32 v168, 31, v48
	s_add_i32 s41, s44, s40
	v_lshl_or_b32 v8, v0, 5, v168
	v_add_u32_e32 v171, s41, v8
	v_add_u32_e32 v8, s40, v8
	s_add_i32 s45, 0, 0x14000
	v_ashrrev_i32_e32 v9, 31, v8
	v_bfe_u32 v169, v48, 5, 1
	v_lshl_add_u32 v170, v0, 9, s45
	v_mov_b64_e32 v[0:1], s[38:39]
	s_movk_i32 s38, 0xa00
	v_lshlrev_b64 v[8:9], 8, v[8:9]
	v_mad_i64_i32 v[0:1], s[38:39], v171, s38, v[0:1]
	v_lshlrev_b32_e32 v194, 4, v169
	v_lshl_add_u64 v[8:9], s[50:51], 0, v[8:9]
	v_lshlrev_b32_e32 v18, 6, v169
	v_mov_b32_e32 v19, v195
	v_lshl_add_u64 v[4:5], v[0:1], 0, v[194:195]
	v_lshl_add_u64 v[8:9], v[8:9], 0, v[18:19]
	global_load_dwordx4 v[124:127], v[4:5], off
	global_load_dwordx4 v[120:123], v[4:5], off offset:32
	global_load_dwordx4 v[116:119], v[4:5], off offset:64
	global_load_dwordx4 v[112:115], v[4:5], off offset:96
	global_load_dwordx4 v[108:111], v[4:5], off offset:128
	global_load_dwordx4 v[104:107], v[4:5], off offset:160
	global_load_dwordx4 v[100:103], v[4:5], off offset:192
	global_load_dwordx4 v[96:99], v[4:5], off offset:224
	global_load_dwordx4 v[10:13], v[4:5], off offset:256
	global_load_dwordx4 v[0:3], v[4:5], off offset:288
	global_load_dwordx4 v[14:17], v[4:5], off offset:320
	s_nop 0
	global_load_dwordx4 v[4:7], v[4:5], off offset:352
	v_ashrrev_i32_e32 v53, 4, v48
	global_load_dwordx2 v[18:19], v[8:9], off
	global_load_dwordx4 v[128:131], v[8:9], off
	global_load_dwordx4 v[132:135], v[8:9], off offset:16
	global_load_dwordx4 v[136:139], v[8:9], off offset:32
	global_load_dwordx4 v[140:143], v[8:9], off offset:48
	global_load_dwordx4 v[222:225], v[8:9], off offset:128
	global_load_dwordx4 v[226:229], v[8:9], off offset:144
	global_load_dwordx4 v[230:233], v[8:9], off offset:160
	global_load_dwordx4 v[234:237], v[8:9], off offset:176
	v_add_u32_e32 v54, 32, v53
	v_and_b32_e32 v49, 63, v48
	v_add_u32_e32 v50, s44, v53
	v_ashrrev_i32_e32 v55, 3, v48
	s_cmp_lg_u32 0, -1
	s_movk_i32 s38, 0x70
	s_cselect_b32 s46, 0, 0
	s_add_i32 s45, 0, 0x10000
	v_lshlrev_b32_e32 v75, 8, v168
	v_or_b32_e32 v84, 32, v194
	v_or_b32_e32 v85, 64, v194
	v_or_b32_e32 v86, 0x60, v194
	s_mov_b32 s81, s80
	s_mov_b32 s82, s80
	s_mov_b32 s83, s80
	s_mov_b32 s84, s80
	s_mov_b32 s85, s80
	s_mov_b32 s86, s80
	s_mov_b32 s87, s80
	s_mov_b32 s88, s80
	s_mov_b32 s89, s80
	s_mov_b32 s90, s80
	s_mov_b32 s91, s80
	s_mov_b32 s92, s80
	s_mov_b32 s93, s80
	s_mov_b32 s94, s80
	s_mov_b32 s95, s80
	s_mov_b32 s71, 2
	v_lshl_add_u32 v173, v168, 2, v170
	v_mov_b32_e32 v179, 0
	s_waitcnt vmcnt(4)
	v_lshlrev_b32_e32 v20, 16, v10
	s_waitcnt vmcnt(2)
	v_lshlrev_b32_e32 v21, 16, v14
	s_waitcnt vmcnt(0)
	v_pk_mul_f32 v[22:23], v[18:19], v[20:21]
	v_pk_mul_f32 v[18:19], v[18:19], v[20:21] op_sel:[1,0] op_sel_hi:[0,1]
	v_add_f32_e32 v18, v18, v19
	v_sub_f32_e32 v22, v22, v23
	v_cvt_pk_bf16_f32 v57, v22, v18
	v_mov_b32_e32 v18, v130
	v_mov_b32_e32 v19, v131
	v_and_b32_e32 v21, 0xffff0000, v14
	v_and_b32_e32 v20, 0xffff0000, v10
	s_waitcnt vmcnt(0)
	v_pk_mul_f32 v[22:23], v[18:19], v[20:21]
	v_pk_mul_f32 v[18:19], v[18:19], v[20:21] op_sel:[0,1] op_sel_hi:[1,0]
	v_sub_f32_e32 v10, v22, v23
	v_add_f32_e32 v14, v18, v19
	v_cvt_pk_bf16_f32 v58, v10, v14
	v_mov_b32_e32 v18, v132
	v_mov_b32_e32 v19, v133
	v_lshlrev_b32_e32 v21, 16, v15
	v_lshlrev_b32_e32 v20, 16, v11
	v_and_b32_e32 v15, 0xffff0000, v15
	s_waitcnt vmcnt(0)
	v_pk_mul_f32 v[22:23], v[18:19], v[20:21]
	v_pk_mul_f32 v[18:19], v[18:19], v[20:21] op_sel:[0,1] op_sel_hi:[1,0]
	v_sub_f32_e32 v10, v22, v23
	v_add_f32_e32 v14, v18, v19
	v_cvt_pk_bf16_f32 v59, v10, v14
	v_mov_b32_e32 v18, v134
	v_mov_b32_e32 v19, v135
	v_and_b32_e32 v14, 0xffff0000, v11
	s_waitcnt vmcnt(0)
	v_pk_mul_f32 v[10:11], v[18:19], v[14:15]
	s_nop 0
	v_sub_f32_e32 v20, v10, v11
	v_pk_mul_f32 v[10:11], v[18:19], v[14:15] op_sel:[0,1] op_sel_hi:[1,0]
	v_lshlrev_b32_e32 v15, 16, v16
	v_add_f32_e32 v10, v10, v11
	v_cvt_pk_bf16_f32 v60, v20, v10
	v_mov_b32_e32 v10, v136
	v_mov_b32_e32 v11, v137
	v_lshlrev_b32_e32 v14, 16, v12
	s_waitcnt vmcnt(0)
	v_pk_mul_f32 v[18:19], v[10:11], v[14:15]
	v_pk_mul_f32 v[10:11], v[10:11], v[14:15] op_sel:[0,1] op_sel_hi:[1,0]
	v_sub_f32_e32 v18, v18, v19
	v_add_f32_e32 v10, v10, v11
	v_cvt_pk_bf16_f32 v61, v18, v10
	v_mov_b32_e32 v10, v138
	v_mov_b32_e32 v11, v139
	v_and_b32_e32 v15, 0xffff0000, v16
	v_and_b32_e32 v14, 0xffff0000, v12
	v_lshlrev_b32_e32 v16, 4, v48
	v_and_b32_e32 v62, 0x70, v16
	v_bitop3_b32 v76, v84, v75, v62 bitop3:0xde
	v_add_u32_e32 v181, 0, v76
	s_waitcnt vmcnt(0)
	v_pk_mul_f32 v[18:19], v[10:11], v[14:15]
	v_pk_mul_f32 v[10:11], v[10:11], v[14:15] op_sel:[0,1] op_sel_hi:[1,0]
	v_sub_f32_e32 v12, v18, v19
	v_add_f32_e32 v10, v10, v11
	v_cvt_pk_bf16_f32 v63, v12, v10
	v_mov_b32_e32 v10, v140
	v_mov_b32_e32 v11, v141
	v_lshlrev_b32_e32 v15, 16, v17
	v_lshlrev_b32_e32 v14, 16, v13
	s_waitcnt vmcnt(0)
; __device__ __forceinline__ unsigned cvt_pk_bf16(float lo, float hi) { unsigned r; asm volatile("v_cvt_pk_bf16_f32 %0, %1, %2" : "=v"(r) : "v"(lo), "v"(hi)); return r; }
; __device__ __forceinline__ float bf2f(unsigned short h) { return __uint_as_float(((unsigned)h) << 16); }
; __device__ __forceinline__ int v_st(int k, int c) { const int kk = (k & ~0xC) | ((k & 4) << 1) | ((k & 8) >> 1); return ((kk >> 3) * 4 + (c >> 5)) * 512 + ((kk & 7) * 32 + (c & 31)) * 2; }
; __device__ __forceinline__ int v_rd_base(int lane) { return ((lane & 3) << 3) | (((lane >> 2) & 3) << 6) | (((lane >> 4) & 1) << 5) | (((lane >> 5) & 1) << 8); }
; #define SWRITE(b, i) do { *(bf16x8*)(V_lds + (b) * SHM_V + vst0) = sr_[i].vs0; *(bf16x8*)(V_lds + (b) * SHM_V + vst1) = sr_[i].vs1; const int kc = sc * 2; \
;     *(bf16x8*)(K_lds + (b) * SHM_K + KSWZ(sr, kc)) = sr_[i].ks0; *(bf16x8*)(K_lds + (b) * SHM_K + KSWZ(32 + sr, kc)) = sr_[i].ks1; \
;     if constexpr (MODE == 1) *(bf16x8*)(KR_lds + (b) * SHM_KR + KRSWZ(krr, krc * 2)) = sr_[i].kr; } while (0)
; template <int MODE>
; __device__ __forceinline__ void body(const Desc& d, char* lds, int wave_id) {
;     ...
;       for (int dd = 0; dd < 2; ++dd) { bf16x8 x1 = qr[8 + dd], x2 = qr[10 + dd]; bf16x8 y1, y2;
; #pragma unroll
;         for (int e = 0; e < 8; ++e) { const f32x2 cs = rp[dd * 16 + e]; const float a = bf2f((unsigned short)x1[e]), b = bf2f((unsigned short)x2[e]);
;           const float o1 = a * cs.x - b * cs.y, o2 = b * cs.x + a * cs.y; const unsigned pk = cvt_pk_bf16(o1, o2); y1[e] = (short)(pk & 0xffff); y2[e] = (short)(pk >> 16); }
;         qr[8 + dd] = y1; qr[10 + dd] = y2; }
;     ...
;   const int sr = tid >> 4, sc = (tid & 15) * 8, vst0 = v_st(sr, sc), vst1 = v_st(32 + sr, sc);
;   const int krr = tid >> 3, krc = (tid & 7) * 8;
;   const int vb0 = (int)(uintptr_t)V_lds + v_rd_base(lane);
;   struct { bf16x8 vs0, vs1, ks0, ks1, kr; } sr_[1];
;     ...
;   f32x16 pA0, pA1, pB0, pB1; float mnA, mnB, alA, alB; bf16x8 pa0, pa1, pa2, pa3; const int NT = d.NT;
;   const int tlo_ = __builtin_amdgcn_readfirstlane(wid) >> 1;
;     ...
;   constexpr int SE = 0, SO = 0;
;   SLOAD(SE, 0); asm volatile("s_waitcnt vmcnt(0)" ::: "memory"); SWRITE(0, SE); __syncthreads();
	v_pk_mul_f32 v[18:19], v[10:11], v[14:15]
	v_pk_mul_f32 v[10:11], v[10:11], v[14:15] op_sel:[0,1] op_sel_hi:[1,0]
	v_sub_f32_e32 v12, v18, v19
	v_add_f32_e32 v10, v10, v11
	v_cvt_pk_bf16_f32 v65, v12, v10
	v_mov_b32_e32 v10, v142
	v_mov_b32_e32 v11, v143
	v_and_b32_e32 v15, 0xffff0000, v17
	v_and_b32_e32 v14, 0xffff0000, v13
	v_add_u32_e32 v17, s44, v55
	v_lshl_or_b32 v56, v17, 7, v62
	v_add_u32_e32 v220, 0x4000, v56
	s_waitcnt vmcnt(0)
	v_pk_mul_f32 v[12:13], v[10:11], v[14:15]
	v_pk_mul_f32 v[10:11], v[10:11], v[14:15] op_sel:[0,1] op_sel_hi:[1,0]
	v_sub_f32_e32 v12, v12, v13
	v_add_f32_e32 v10, v10, v11
	v_cvt_pk_bf16_f32 v67, v12, v10
	v_mov_b32_e32 v10, v222
	v_mov_b32_e32 v11, v223
	v_lshlrev_b32_e32 v13, 16, v4
	v_lshlrev_b32_e32 v12, 16, v0
	s_waitcnt vmcnt(0)
	v_pk_mul_f32 v[14:15], v[10:11], v[12:13]
	v_pk_mul_f32 v[10:11], v[10:11], v[12:13] op_sel:[0,1] op_sel_hi:[1,0]
	v_sub_f32_e32 v14, v14, v15
	v_add_f32_e32 v10, v10, v11
	v_cvt_pk_bf16_f32 v64, v14, v10
	v_mov_b32_e32 v10, v224
	v_mov_b32_e32 v11, v225
	v_and_b32_e32 v13, 0xffff0000, v4
	v_and_b32_e32 v12, 0xffff0000, v0
	s_waitcnt vmcnt(0)
	v_pk_mul_f32 v[14:15], v[10:11], v[12:13]
	v_pk_mul_f32 v[10:11], v[10:11], v[12:13] op_sel:[0,1] op_sel_hi:[1,0]
	v_sub_f32_e32 v0, v14, v15
	v_add_f32_e32 v4, v10, v11
	v_cvt_pk_bf16_f32 v66, v0, v4
	v_mov_b32_e32 v10, v226
	v_mov_b32_e32 v11, v227
	v_lshlrev_b32_e32 v13, 16, v5
	v_lshlrev_b32_e32 v12, 16, v1
	v_and_b32_e32 v5, 0xffff0000, v5
	s_waitcnt vmcnt(0)
	v_pk_mul_f32 v[14:15], v[10:11], v[12:13]
	v_pk_mul_f32 v[10:11], v[10:11], v[12:13] op_sel:[0,1] op_sel_hi:[1,0]
	v_sub_f32_e32 v0, v14, v15
	v_add_f32_e32 v4, v10, v11
	v_cvt_pk_bf16_f32 v68, v0, v4
	v_mov_b32_e32 v10, v228
	v_mov_b32_e32 v11, v229
	v_and_b32_e32 v4, 0xffff0000, v1
	s_waitcnt vmcnt(0)
	v_pk_mul_f32 v[0:1], v[10:11], v[4:5]
	s_nop 0
	v_sub_f32_e32 v12, v0, v1
	v_pk_mul_f32 v[0:1], v[10:11], v[4:5] op_sel:[0,1] op_sel_hi:[1,0]
	v_lshlrev_b32_e32 v5, 16, v6
	v_add_f32_e32 v0, v0, v1
	v_cvt_pk_bf16_f32 v69, v12, v0
	v_mov_b32_e32 v0, v230
	v_mov_b32_e32 v1, v231
	v_lshlrev_b32_e32 v4, 16, v2
	s_waitcnt vmcnt(0)
	v_pk_mul_f32 v[10:11], v[0:1], v[4:5]
	v_pk_mul_f32 v[0:1], v[0:1], v[4:5] op_sel:[0,1] op_sel_hi:[1,0]
	v_sub_f32_e32 v10, v10, v11
	v_add_f32_e32 v0, v0, v1
	v_cvt_pk_bf16_f32 v70, v10, v0
	v_mov_b32_e32 v0, v232
	v_mov_b32_e32 v1, v233
	v_and_b32_e32 v5, 0xffff0000, v6
	v_and_b32_e32 v4, 0xffff0000, v2
	s_waitcnt vmcnt(0)
	v_pk_mul_f32 v[10:11], v[0:1], v[4:5]
	v_pk_mul_f32 v[0:1], v[0:1], v[4:5] op_sel:[0,1] op_sel_hi:[1,0]
	v_sub_f32_e32 v2, v10, v11
	v_add_f32_e32 v0, v0, v1
	v_cvt_pk_bf16_f32 v71, v2, v0
	v_mov_b32_e32 v0, v234
	v_mov_b32_e32 v1, v235
	v_lshlrev_b32_e32 v5, 16, v7
	v_lshlrev_b32_e32 v4, 16, v3
	s_waitcnt vmcnt(0)
	v_pk_mul_f32 v[10:11], v[0:1], v[4:5]
	v_pk_mul_f32 v[0:1], v[0:1], v[4:5] op_sel:[0,1] op_sel_hi:[1,0]
	v_sub_f32_e32 v2, v10, v11
	v_add_f32_e32 v0, v0, v1
	v_cvt_pk_bf16_f32 v72, v2, v0
	v_mov_b32_e32 v0, v236
	v_mov_b32_e32 v1, v237
	v_and_b32_e32 v5, 0xffff0000, v7
	v_and_b32_e32 v4, 0xffff0000, v3
	s_waitcnt vmcnt(0)
	v_pk_mul_f32 v[2:3], v[0:1], v[4:5]
	s_nop 0
	v_sub_f32_e32 v2, v2, v3
	v_pk_mul_f32 v[0:1], v[0:1], v[4:5] op_sel:[0,1] op_sel_hi:[1,0]
	v_and_b32_e32 v3, 3, v53
	v_add_f32_e32 v0, v0, v1
	v_cvt_pk_bf16_f32 v73, v2, v0
	v_and_b32_e32 v1, 0xfffff0, v53
	v_lshlrev_b32_e32 v2, 1, v53
	v_lshlrev_b32_e32 v0, 3, v48
	v_and_or_b32 v1, v2, 8, v1
	v_and_b32_e32 v52, 0x78, v0
	v_lshrrev_b32_e32 v2, 1, v53
	v_lshrrev_b32_e32 v1, 1, v1
	v_bfe_u32 v0, v0, 5, 2
	v_or_b32_e32 v1, v1, v0
	v_and_or_b32 v2, v2, 4, v3
	v_lshlrev_b32_e32 v20, 1, v52
	v_lshlrev_b32_e32 v1, 9, v1
	v_lshlrev_b32_e32 v2, 6, v2
	v_and_b32_e32 v3, 48, v20
	v_or3_b32 v21, v1, v2, v3
	v_and_b32_e32 v1, 0xfffff0, v54
	v_lshlrev_b32_e32 v4, 1, v54
	v_and_or_b32 v1, v4, 8, v1
	v_lshrrev_b32_e32 v1, 1, v1
	v_or_b32_e32 v0, v1, v0
	v_lshlrev_b32_e32 v0, 9, v0
	v_or3_b32 v22, v0, v2, v3
	v_lshlrev_b32_e32 v0, 3, v49
	v_and_b32_e32 v1, 0xc0, v16
	v_lshlrev_b32_e32 v2, 1, v48
	v_and_or_b32 v1, v0, 24, v1
	v_and_b32_e32 v2, 32, v2
	v_and_b32_e32 v0, 0x100, v0
	v_or3_b32 v51, v1, v2, v0
	v_mul_lo_u32 v0, v50, s97
	v_or_b32_e32 v0, v0, v52
	v_lshlrev_b32_e32 v8, 1, v0
	v_add_u32_e32 v0, s44, v54
	v_mul_lo_u32 v0, v0, s97
	v_or_b32_e32 v0, v0, v52
	v_lshlrev_b32_e32 v12, 1, v0
	global_load_dwordx4 v[0:3], v8, s[60:61] offset:256
	global_load_dwordx4 v[4:7], v12, s[60:61] offset:256
	s_nop 0
	global_load_dwordx4 v[8:11], v8, s[60:61]
	s_nop 0
	global_load_dwordx4 v[12:15], v12, s[60:61]
	v_add_u32_e32 v174, 0, v21
	global_load_dwordx4 v[16:19], v56, s[48:49]
	s_waitcnt vmcnt(0)
	v_add_u32_e32 v175, 0, v22
	v_add_u32_e32 v172, s46, v51
	s_waitcnt vmcnt(4)
	ds_write_b128 v174, v[0:3]
	v_lshlrev_b32_e32 v0, 8, v53
	v_and_b32_e32 v1, 0x70, v48
	v_bitop3_b32 v0, v20, v0, v1 bitop3:0xde
	v_add_u32_e32 v177, 0, v0
	v_lshlrev_b32_e32 v0, 8, v54
	v_bitop3_b32 v0, v20, v0, v1 bitop3:0xde
	v_xor_b32_e32 v1, v55, v48
	v_add_u32_e32 v178, 0, v0
	v_lshlrev_b32_e32 v0, 7, v55
	v_lshlrev_b32_e32 v1, 4, v1
	v_and_or_b32 v74, v1, s38, v0
	v_add_u32_e32 v0, s45, v74
	s_waitcnt vmcnt(3)
	ds_write_b128 v175, v[4:7]
	s_waitcnt vmcnt(2)
	ds_write_b128 v177, v[8:11] offset:32768
	s_waitcnt vmcnt(1)
	ds_write_b128 v178, v[12:15] offset:32768
	s_waitcnt vmcnt(0)
	ds_write_b128 v0, v[16:19]
	v_bitop3_b32 v0, v194, v75, v62 bitop3:0xde
	v_add_u32_e32 v180, 0, v0
	s_waitcnt lgkmcnt(0)
	s_barrier
; #define QKT(P0, P1, b, t) do { qkt<NQ>(P0, P1, K_lds + (b) * SHM_K, KR_lds + (b) * SHM_KR, qr, r32, hi); mask_tile<MODE>(P0, P1, d, t, vq, hi); } while (0)
; template <int NQ>
; __device__ __forceinline__ void qkt(f32x16& p0, f32x16& p1, const char* Ks, const char* KRs, const bf16x8* qr, int r32, int hi) {
;   p0 = f32x16{}; p1 = f32x16{};
; #pragma unroll
;   for (int d0 = 0; d0 < 8; ++d0) { const int cb = (d0 * 16 + hi * 8) * 2;
;     bf16x8 b0 = *reinterpret_cast<const bf16x8*>(Ks + KSWZ(r32, cb));
;     bf16x8 b1 = *reinterpret_cast<const bf16x8*>(Ks + KSWZ(32 + r32, cb));
;     p0 = __builtin_amdgcn_mfma_f32_32x32x16_bf16(b0, qr[d0], p0, 0, 0, 0);
;     p1 = __builtin_amdgcn_mfma_f32_32x32x16_bf16(b1, qr[d0], p1, 0, 0, 0); }
;   if constexpr (NQ == 12) {
; #pragma unroll
;     for (int d0 = 0; d0 < 4; ++d0) { const int cb = d0 * 32 + hi * 16;
;       bf16x8 b0 = *reinterpret_cast<const bf16x8*>(KRs + KRSWZ(r32, cb));
;       bf16x8 b1 = *reinterpret_cast<const bf16x8*>(KRs + KRSWZ(32 + r32, cb));
;       p0 = __builtin_amdgcn_mfma_f32_32x32x16_bf16(b0, qr[8 + d0], p0, 0, 0, 0);
;       p1 = __builtin_amdgcn_mfma_f32_32x32x16_bf16(b1, qr[8 + d0], p1, 0, 0, 0); }
;   }
; template <int MODE>
; __device__ __forceinline__ void body(const Desc& d, char* lds, int wave_id) {
;     ...
;   if (ACT(0)) { QKT(pA0, pA1, 0, 0); partialSM(pA0, pA1, m_reg, mnA, alA, d.C, d.THRS); }
	ds_read_b128 v[16:19], v180 offset:32768
	ds_read_b128 v[20:23], v180 offset:40960
	s_waitcnt lgkmcnt(1)
	v_mfma_f32_32x32x16_bf16 v[32:47], v[16:19], v[124:127], 0
	ds_read_b128 v[76:79], v181 offset:32768
	ds_read_b128 v[80:83], v181 offset:40960
	s_mov_b32 s38, 0x5040100
	v_perm_b32 v128, v58, v57, s38
	v_perm_b32 v129, v60, v59, s38
	v_perm_b32 v130, v63, v61, s38
	v_perm_b32 v131, v67, v65, s38
	v_perm_b32 v132, v66, v64, s38
	s_waitcnt lgkmcnt(2)
	v_mfma_f32_32x32x16_bf16 v[16:31], v[20:23], v[124:127], 0
	v_perm_b32 v133, v69, v68, s38
	v_perm_b32 v134, v71, v70, s38
	v_perm_b32 v135, v73, v72, s38
	s_mov_b32 s38, 0x7060302
	v_perm_b32 v136, v58, v57, s38
	v_perm_b32 v137, v60, v59, s38
	v_perm_b32 v138, v63, v61, s38
	s_waitcnt lgkmcnt(1)
	v_mfma_f32_32x32x16_bf16 v[32:47], v[76:79], v[120:123], v[32:47]
	v_bitop3_b32 v76, v85, v75, v62 bitop3:0xde
	v_add_u32_e32 v182, 0, v76
	v_perm_b32 v139, v67, v65, s38
	v_perm_b32 v140, v66, v64, s38
	v_perm_b32 v141, v69, v68, s38
	v_perm_b32 v142, v71, v70, s38
	v_perm_b32 v143, v73, v72, s38
	s_waitcnt lgkmcnt(0)
	v_mfma_f32_32x32x16_bf16 v[16:31], v[80:83], v[120:123], v[16:31]
	ds_read_b128 v[76:79], v182 offset:32768
	ds_read_b128 v[80:83], v182 offset:40960
	v_mov_b64_e32 v[0:1], s[80:81]
	v_add_u32_e32 v218, 0, v74
	v_mov_b64_e32 v[14:15], s[94:95]
	v_add_u32_e32 v219, 0x12000, v218
	v_mov_b64_e32 v[2:3], s[82:83]
	v_mov_b64_e32 v[4:5], s[84:85]
	s_waitcnt lgkmcnt(1)
	v_mfma_f32_32x32x16_bf16 v[32:47], v[76:79], v[116:119], v[32:47]
	v_bitop3_b32 v76, v86, v75, v62 bitop3:0xde
	v_add_u32_e32 v183, 0, v76
	v_mov_b64_e32 v[6:7], s[86:87]
	v_mov_b64_e32 v[8:9], s[88:89]
	v_mov_b64_e32 v[10:11], s[90:91]
	v_mov_b64_e32 v[12:13], s[92:93]
	v_readlane_b32 s94, v255, 11
	s_waitcnt lgkmcnt(0)
	v_mfma_f32_32x32x16_bf16 v[16:31], v[80:83], v[116:119], v[16:31]
	ds_read_b128 v[76:79], v183 offset:32768
	ds_read_b128 v[80:83], v183 offset:40960
	s_mov_b32 s92, 0x6dc9c883
	v_readlane_b32 s95, v255, 12
	s_mov_b32 s93, 0x3fc45f30
	s_mov_b32 s91, 0x9fff
	s_mov_b32 s90, 0x8b00000
	s_waitcnt lgkmcnt(1)
	v_mfma_f32_32x32x16_bf16 v[32:47], v[76:79], v[112:115], v[32:47]
	v_or_b32_e32 v76, 0x80, v194
	v_bitop3_b32 v76, v76, v75, v62 bitop3:0xde
	v_add_u32_e32 v184, 0, v76
	s_waitcnt lgkmcnt(0)
	v_mfma_f32_32x32x16_bf16 v[16:31], v[80:83], v[112:115], v[16:31]
	ds_read_b128 v[76:79], v184 offset:32768
	ds_read_b128 v[80:83], v184 offset:40960
	s_waitcnt lgkmcnt(1)
	v_mfma_f32_32x32x16_bf16 v[32:47], v[76:79], v[108:111], v[32:47]
	v_or_b32_e32 v76, 0xa0, v194
	v_bitop3_b32 v76, v76, v75, v62 bitop3:0xde
	v_add_u32_e32 v185, 0, v76
	s_waitcnt lgkmcnt(0)
	v_mfma_f32_32x32x16_bf16 v[16:31], v[80:83], v[108:111], v[16:31]
	ds_read_b128 v[76:79], v185 offset:32768
	ds_read_b128 v[80:83], v185 offset:40960
	s_waitcnt lgkmcnt(1)
	v_mfma_f32_32x32x16_bf16 v[32:47], v[76:79], v[104:107], v[32:47]
	v_or_b32_e32 v76, 0xc0, v194
	v_bitop3_b32 v76, v76, v75, v62 bitop3:0xde
	v_add_u32_e32 v186, 0, v76
	s_waitcnt lgkmcnt(0)
	v_mfma_f32_32x32x16_bf16 v[16:31], v[80:83], v[104:107], v[16:31]
	ds_read_b128 v[76:79], v186 offset:32768
	ds_read_b128 v[80:83], v186 offset:40960
	s_waitcnt lgkmcnt(1)
	v_mfma_f32_32x32x16_bf16 v[32:47], v[76:79], v[100:103], v[32:47]
	v_or_b32_e32 v76, 0xe0, v194
	v_bitop3_b32 v75, v76, v75, v62 bitop3:0xde
	v_add_u32_e32 v187, 0, v75
	v_lshlrev_b32_e32 v75, 7, v168
	v_bitop3_b32 v188, v194, v75, v62 bitop3:0xde
	v_add_u32_e32 v189, s45, v188
	v_bitop3_b32 v190, v84, v75, v62 bitop3:0xde
	s_waitcnt lgkmcnt(0)
	v_mfma_f32_32x32x16_bf16 v[16:31], v[80:83], v[100:103], v[16:31]
	ds_read_b128 v[76:79], v187 offset:32768
	ds_read_b128 v[80:83], v187 offset:40960
	v_add_u32_e32 v191, s45, v190
	v_bitop3_b32 v192, v85, v75, v62 bitop3:0xde
	v_add_u32_e32 v193, s45, v192
	v_bitop3_b32 v214, v86, v75, v62 bitop3:0xde
	v_add_u32_e32 v215, s45, v214
	s_waitcnt lgkmcnt(1)
	v_mfma_f32_32x32x16_bf16 v[32:47], v[76:79], v[96:99], v[32:47]
	s_waitcnt lgkmcnt(0)
	v_mfma_f32_32x32x16_bf16 v[16:31], v[80:83], v[96:99], v[16:31]
	ds_read_b128 v[76:79], v189
	ds_read_b128 v[80:83], v189 offset:4096
	s_waitcnt lgkmcnt(1)
	v_mfma_f32_32x32x16_bf16 v[32:47], v[76:79], v[128:131], v[32:47]
	s_waitcnt lgkmcnt(0)
	v_mfma_f32_32x32x16_bf16 v[16:31], v[80:83], v[128:131], v[16:31]
	ds_read_b128 v[76:79], v191
	ds_read_b128 v[80:83], v191 offset:4096
	s_waitcnt lgkmcnt(1)
	v_mfma_f32_32x32x16_bf16 v[32:47], v[76:79], v[132:135], v[32:47]
	s_waitcnt lgkmcnt(0)
	v_mfma_f32_32x32x16_bf16 v[16:31], v[80:83], v[132:135], v[16:31]
	ds_read_b128 v[76:79], v193
	ds_read_b128 v[80:83], v193 offset:4096
	s_waitcnt lgkmcnt(1)
	v_mfma_f32_32x32x16_bf16 v[32:47], v[76:79], v[136:139], v[32:47]
	ds_read_b128 v[58:61], v215
	ds_read_b128 v[76:79], v215 offset:4096
	s_waitcnt lgkmcnt(1)
; #define SWRITE(b, i) do { *(bf16x8*)(V_lds + (b) * SHM_V + vst0) = sr_[i].vs0; *(bf16x8*)(V_lds + (b) * SHM_V + vst1) = sr_[i].vs1; const int kc = sc * 2; \
;     *(bf16x8*)(K_lds + (b) * SHM_K + KSWZ(sr, kc)) = sr_[i].ks0; *(bf16x8*)(K_lds + (b) * SHM_K + KSWZ(32 + sr, kc)) = sr_[i].ks1; \
;     if constexpr (MODE == 1) *(bf16x8*)(KR_lds + (b) * SHM_KR + KRSWZ(krr, krc * 2)) = sr_[i].kr; } while (0)
; #define SWAIT() asm volatile("s_waitcnt vmcnt(0)" ::: "memory")
; __device__ __forceinline__ void partialSM(f32x16& p0, f32x16& p1, float& m_reg, float& mn, float& alpha, const float C, const float THRS) {
;   float pmax = p0[0];
; #pragma unroll
;   for (int r = 1; r < 16; ++r) pmax = fmaxf(pmax, p0[r]);
; #pragma unroll
;   for (int r = 0; r < 16; ++r) pmax = fmaxf(pmax, p1[r]);
;   { auto rr = __builtin_amdgcn_permlane32_swap(__float_as_uint(pmax), __float_as_uint(pmax), false, false);
;     pmax = fmaxf(__uint_as_float(rr[0]), __uint_as_float(rr[1])); }
;   if (__builtin_expect(__all(pmax - m_reg <= THRS), 1)) { mn = m_reg; alpha = 1.f; }
;   else { mn = fmaxf(m_reg, pmax); alpha = __builtin_amdgcn_exp2f((m_reg - mn) * C); m_reg = mn; }
;   const float mnC = -mn * C;
; #pragma unroll
;   for (int r = 0; r < 16; ++r) p0[r] = fmaf(p0[r], C, mnC);
; #pragma unroll
;   for (int r = 0; r < 16; ++r) p1[r] = fmaf(p1[r], C, mnC);
; #pragma unroll
;   for (int r = 0; r < 16; ++r) p0[r] = __builtin_amdgcn_exp2f(p0[r]);
; }
; template <int MODE>
; __device__ __forceinline__ void body(const Desc& d, char* lds, int wave_id) {
;     ...
;   SLOAD(SO, 1);
;   SWAIT(); SWRITE(1, SO); __syncthreads();
	v_mfma_f32_32x32x16_bf16 v[32:47], v[58:61], v[140:143], v[32:47]
	v_mfma_f32_32x32x16_bf16 v[16:31], v[80:83], v[136:139], v[16:31]
	s_nop 10
	v_max_f32_e32 v57, v33, v33
	v_max_f32_e32 v58, v32, v32
	v_max_f32_e32 v57, v58, v57
	v_max3_f32 v57, v57, v34, v35
	v_max3_f32 v57, v57, v36, v37
	v_max3_f32 v57, v57, v38, v39
	v_max3_f32 v57, v57, v40, v41
	s_waitcnt lgkmcnt(0)
	v_mfma_f32_32x32x16_bf16 v[16:31], v[76:79], v[140:143], v[16:31]
	v_max3_f32 v57, v57, v42, v43
	v_max3_f32 v57, v57, v44, v45
	v_max3_f32 v57, v57, v46, v47
	s_nop 8
	v_max3_f32 v57, v57, v16, v17
	v_max3_f32 v57, v57, v18, v19
	v_max3_f32 v57, v57, v20, v21
	v_max3_f32 v57, v57, v22, v23
	v_max3_f32 v57, v57, v24, v25
	v_max3_f32 v57, v57, v26, v27
	v_max3_f32 v57, v57, v28, v29
	v_max3_f32 v57, v57, v30, v31
	v_mov_b32_e32 v58, v57
	s_nop 1
	v_permlane32_swap_b32_e32 v57, v58
	v_max_f32_e32 v58, v58, v58
	v_max_f32_e32 v57, v57, v57
	v_max_f32_e32 v57, v57, v58
	v_add_f32_e32 v58, 0x7149f2ca, v57
	v_max_f32_e32 v57, 0xf149f2ca, v57
	v_cmp_ge_f32_e32 vcc, s13, v58
	v_sub_f32_e32 v58, 0xf149f2ca, v57
	v_mul_f32_e32 v58, 0x3dd53b94, v58
	v_exp_f32_e32 v58, v58
	s_cmp_eq_u64 vcc, exec
	s_cselect_b64 vcc, -1, 0
	v_cndmask_b32_e32 v217, v57, v209, vcc
	v_cndmask_b32_e64 v216, v58, 1.0, vcc
	v_mul_f32_e32 v58, 0xbdd53b94, v217
	s_or_b32 s38, s44, 64
	v_pk_fma_f32 v[156:157], v[16:17], s[16:17], v[58:59] op_sel_hi:[1,0,0]
	v_add_u32_e32 v16, s38, v53
	v_mul_lo_u32 v16, v16, s97
	v_or_b32_e32 v16, v16, v52
	v_pk_fma_f32 v[144:145], v[24:25], s[16:17], v[58:59] op_sel_hi:[1,0,0]
	v_lshlrev_b32_e32 v24, 1, v16
	v_add_u32_e32 v16, s38, v54
	v_mul_lo_u32 v16, v16, s97
	v_fmamk_f32 v32, v32, 0x3dd53b94, v58
	v_or_b32_e32 v16, v16, v52
	v_pk_fma_f32 v[152:153], v[28:29], s[16:17], v[58:59] op_sel_hi:[1,0,0]
	v_exp_f32_e32 v235, v32
	v_lshlrev_b32_e32 v28, 1, v16
	v_add_u32_e32 v32, s38, v55
	v_fmamk_f32 v33, v33, 0x3dd53b94, v58
	v_fmamk_f32 v34, v34, 0x3dd53b94, v58
	v_fmamk_f32 v35, v35, 0x3dd53b94, v58
	v_pk_fma_f32 v[150:151], v[30:31], s[16:17], v[58:59] op_sel_hi:[1,0,0]
	v_pk_fma_f32 v[158:159], v[26:27], s[16:17], v[58:59] op_sel_hi:[1,0,0]
	v_pk_fma_f32 v[146:147], v[22:23], s[16:17], v[58:59] op_sel_hi:[1,0,0]
	v_pk_fma_f32 v[148:149], v[20:21], s[16:17], v[58:59] op_sel_hi:[1,0,0]
	v_pk_fma_f32 v[154:155], v[18:19], s[16:17], v[58:59] op_sel_hi:[1,0,0]
	global_load_dwordx4 v[16:19], v24, s[60:61] offset:256
	global_load_dwordx4 v[20:23], v28, s[60:61] offset:256
	s_nop 0
	global_load_dwordx4 v[24:27], v24, s[60:61]
	s_nop 0
	global_load_dwordx4 v[28:31], v28, s[60:61]
	v_lshl_or_b32 v32, v32, 7, v62
	v_exp_f32_e32 v237, v33
	v_exp_f32_e32 v165, v34
	v_exp_f32_e32 v236, v35
	global_load_dwordx4 v[32:35], v32, s[48:49]
	v_mov_b32_e32 v57, v58
	v_fmamk_f32 v36, v36, 0x3dd53b94, v58
	v_fmamk_f32 v37, v37, 0x3dd53b94, v58
	v_fmamk_f32 v38, v38, 0x3dd53b94, v58
	v_fmamk_f32 v39, v39, 0x3dd53b94, v58
	v_fmamk_f32 v40, v40, 0x3dd53b94, v58
	v_fmamk_f32 v41, v41, 0x3dd53b94, v58
	v_fmamk_f32 v42, v42, 0x3dd53b94, v58
	v_fmamk_f32 v43, v43, 0x3dd53b94, v58
	v_fmamk_f32 v44, v44, 0x3dd53b94, v58
	v_fmamk_f32 v45, v45, 0x3dd53b94, v58
	v_fmamk_f32 v46, v46, 0x3dd53b94, v58
	v_fmac_f32_e32 v57, 0x3dd53b94, v47
	v_exp_f32_e32 v166, v36
	v_exp_f32_e32 v234, v37
	v_exp_f32_e32 v167, v38
	v_exp_f32_e32 v233, v39
	v_exp_f32_e32 v230, v40
	v_exp_f32_e32 v232, v41
	v_exp_f32_e32 v229, v42
	v_exp_f32_e32 v231, v43
	v_exp_f32_e32 v161, v44
	v_exp_f32_e32 v163, v45
	v_exp_f32_e32 v160, v46
	v_exp_f32_e32 v162, v57
	s_movk_i32 s38, 0xc00
	s_waitcnt vmcnt(0)
	s_waitcnt vmcnt(4)
	ds_write_b128 v174, v[16:19] offset:16384
	s_waitcnt vmcnt(3)
	ds_write_b128 v175, v[20:23] offset:16384
	s_waitcnt vmcnt(2)
	ds_write_b128 v177, v[24:27] offset:49152
	s_waitcnt vmcnt(1)
	ds_write_b128 v178, v[28:31] offset:49152
	s_addk_i32 s46, 0x4000
	v_mul_lo_u32 v16, v50, s38
	v_and_b32_e32 v17, 15, v48
	v_cmp_gt_u32_e64 s[44:45], 32, v49
	s_waitcnt vmcnt(0)
	ds_write_b128 v219, v[32:35]
	v_add_u32_e32 v176, s46, v51
	v_lshl_or_b32 v225, v17, 4, v16
	v_mov_b64_e32 v[46:47], v[14:15]
	v_mov_b64_e32 v[30:31], v[14:15]
	v_mov_b64_e32 v[62:63], v[14:15]
	v_mov_b64_e32 v[44:45], v[12:13]
	v_mov_b64_e32 v[42:43], v[10:11]
	v_mov_b64_e32 v[40:41], v[8:9]
	v_mov_b64_e32 v[38:39], v[6:7]
	v_mov_b64_e32 v[36:37], v[4:5]
	v_mov_b64_e32 v[34:35], v[2:3]
	v_mov_b64_e32 v[32:33], v[0:1]
	v_mov_b64_e32 v[28:29], v[12:13]
	v_mov_b64_e32 v[26:27], v[10:11]
	v_mov_b64_e32 v[24:25], v[8:9]
	v_mov_b64_e32 v[22:23], v[6:7]
	v_mov_b64_e32 v[20:21], v[4:5]
	v_mov_b64_e32 v[18:19], v[2:3]
	v_mov_b64_e32 v[16:17], v[0:1]
	v_mov_b64_e32 v[60:61], v[12:13]
	v_mov_b64_e32 v[58:59], v[10:11]
	v_mov_b64_e32 v[56:57], v[8:9]
	v_mov_b64_e32 v[54:55], v[6:7]
	v_mov_b64_e32 v[52:53], v[4:5]
	v_mov_b64_e32 v[50:51], v[2:3]
	v_mov_b64_e32 v[48:49], v[0:1]
	s_waitcnt lgkmcnt(0)
	s_barrier

; __device__ __forceinline__ unsigned cvt_pk_bf16(float lo, float hi) { unsigned r; asm volatile("v_cvt_pk_bf16_f32 %0, %1, %2" : "=v"(r) : "v"(lo), "v"(hi)); return r; }
; __device__ __forceinline__ float bf2f(unsigned short h) { return __uint_as_float(((unsigned)h) << 16); }
; __device__ __forceinline__ int crow(int r, int hi) { return (r & 3) + 8 * (r >> 2) + 4 * hi; }
; template <int MODE>
; __device__ __forceinline__ void body(const Desc& d, char* lds, int wave_id) {
;     ...
;   if (hi == 0) { li_l[r32] = w3; if (MODE == 0) { al_l[r32] = w1; w2_l[r32] = w2; } }
;   int* tk_l = (int*)(ws + 96); if (hi == 0) tk_l[r32] = qtok;
;   asm volatile("s_waitcnt lgkmcnt(0)" ::: "memory");
; #pragma unroll
;   for (int r = 0; r < 16; ++r) { const int rr = crow(r, hi); const float ww = li_l[rr]; const size_t ob = (size_t)tk_l[rr] * d.ldo + r32;
;     float a1 = 0.f, a2 = 0.f; if (MODE == 0 && d.comb) { a1 = al_l[rr]; a2 = w2_l[rr]; }
; #pragma unroll
;     for (int d0 = 0; d0 < 4; ++d0) { float v = o[d0][r] * ww;
;       if (MODE == 0 && d.comb) v += a1 * bf2f(d.O1[ob + d0 * 32]) + a2 * bf2f(d.O2[ob + d0 * 32]);
;       d.O[ob + d0 * 32] = (bf16_t)(cvt_pk_bf16(v, v) & 0xffff); } }
.LBB0_1046:
	s_or_b64 exec, exec, s[44:45]
	s_waitcnt lgkmcnt(0)
	v_lshl_add_u32 v64, v217, 2, v220
	s_add_u32 s44, s70, s56
	s_addc_u32 s45, s71, s57
	s_add_u32 s42, s72, s56
	s_addc_u32 s43, s73, s57
	s_add_u32 s46, s68, s56
	s_addc_u32 s47, s69, s57
	s_movk_i32 s40, 0x300
	ds_read2_b32 v[176:177], v64 offset0:0 offset1:32
	ds_read2_b32 v[178:179], v64 offset0:64 offset1:96
	ds_read2_b32 v[180:181], v64 offset0:1 offset1:33
	ds_read2_b32 v[182:183], v64 offset0:65 offset1:97
	ds_read2_b32 v[184:185], v64 offset0:2 offset1:34
	ds_read2_b32 v[186:187], v64 offset0:66 offset1:98
	ds_read2_b32 v[188:189], v64 offset0:3 offset1:35
	ds_read2_b32 v[190:191], v64 offset0:67 offset1:99
	s_waitcnt lgkmcnt(0)
	v_mad_i64_i32 v[76:77], s[38:39], v179, s40, 0
	v_or_b32_e32 v76, v76, v214
	v_lshlrev_b64 v[76:77], 1, v[76:77]
	v_lshl_add_u64 v[192:193], s[46:47], 0, v[76:77]
	v_lshl_add_u64 v[246:247], s[44:45], 0, v[76:77]
	v_lshl_add_u64 v[76:77], s[42:43], 0, v[76:77]
	global_load_ushort v144, v[192:193], off
	global_load_ushort v145, v[192:193], off offset:64
	global_load_ushort v146, v[192:193], off offset:128
	global_load_ushort v147, v[192:193], off offset:192
	global_load_ushort v148, v[246:247], off
	global_load_ushort v149, v[246:247], off offset:64
	global_load_ushort v150, v[246:247], off offset:128
	global_load_ushort v151, v[246:247], off offset:192
	v_mad_i64_i32 v[78:79], s[38:39], v183, s40, 0
	v_or_b32_e32 v78, v78, v214
	v_lshlrev_b64 v[78:79], 1, v[78:79]
	v_lshl_add_u64 v[192:193], s[46:47], 0, v[78:79]
	v_lshl_add_u64 v[246:247], s[44:45], 0, v[78:79]
	v_lshl_add_u64 v[78:79], s[42:43], 0, v[78:79]
	global_load_ushort v152, v[192:193], off
	global_load_ushort v153, v[192:193], off offset:64
	global_load_ushort v154, v[192:193], off offset:128
	global_load_ushort v155, v[192:193], off offset:192
	global_load_ushort v156, v[246:247], off
	global_load_ushort v157, v[246:247], off offset:64
	global_load_ushort v158, v[246:247], off offset:128
	global_load_ushort v159, v[246:247], off offset:192
	v_mad_i64_i32 v[80:81], s[38:39], v187, s40, 0
	v_or_b32_e32 v80, v80, v214
	v_lshlrev_b64 v[80:81], 1, v[80:81]
	v_lshl_add_u64 v[192:193], s[46:47], 0, v[80:81]
	v_lshl_add_u64 v[246:247], s[44:45], 0, v[80:81]
	v_lshl_add_u64 v[80:81], s[42:43], 0, v[80:81]
	global_load_ushort v160, v[192:193], off
	global_load_ushort v161, v[192:193], off offset:64
	global_load_ushort v162, v[192:193], off offset:128
	global_load_ushort v163, v[192:193], off offset:192
	global_load_ushort v164, v[246:247], off
	global_load_ushort v165, v[246:247], off offset:64
	global_load_ushort v166, v[246:247], off offset:128
	global_load_ushort v167, v[246:247], off offset:192
	v_mad_i64_i32 v[82:83], s[38:39], v191, s40, 0
	v_or_b32_e32 v82, v82, v214
	v_lshlrev_b64 v[82:83], 1, v[82:83]
	v_lshl_add_u64 v[192:193], s[46:47], 0, v[82:83]
	v_lshl_add_u64 v[246:247], s[44:45], 0, v[82:83]
	v_lshl_add_u64 v[82:83], s[42:43], 0, v[82:83]
	global_load_ushort v168, v[192:193], off
	global_load_ushort v169, v[192:193], off offset:64
	global_load_ushort v170, v[192:193], off offset:128
	global_load_ushort v171, v[192:193], off offset:192
	global_load_ushort v172, v[246:247], off
	global_load_ushort v173, v[246:247], off offset:64
	global_load_ushort v174, v[246:247], off offset:128
	global_load_ushort v175, v[246:247], off offset:192
	ds_read2_b32 v[222:223], v64 offset0:8 offset1:40
	ds_read2_b32 v[224:225], v64 offset0:72 offset1:104
	ds_read2_b32 v[226:227], v64 offset0:9 offset1:41
	ds_read2_b32 v[228:229], v64 offset0:73 offset1:105
	ds_read2_b32 v[230:231], v64 offset0:10 offset1:42
	ds_read2_b32 v[232:233], v64 offset0:74 offset1:106
	ds_read2_b32 v[234:235], v64 offset0:11 offset1:43
	ds_read2_b32 v[236:237], v64 offset0:75 offset1:107
	s_waitcnt lgkmcnt(0)
	v_mad_i64_i32 v[238:239], s[38:39], v225, s40, 0
	v_or_b32_e32 v238, v238, v214
	v_lshlrev_b64 v[238:239], 1, v[238:239]
	v_lshl_add_u64 v[192:193], s[46:47], 0, v[238:239]
	v_lshl_add_u64 v[246:247], s[44:45], 0, v[238:239]
	v_lshl_add_u64 v[238:239], s[42:43], 0, v[238:239]
	global_load_ushort v112, v[192:193], off
	global_load_ushort v113, v[192:193], off offset:64
	global_load_ushort v114, v[192:193], off offset:128
	global_load_ushort v115, v[192:193], off offset:192
	global_load_ushort v116, v[246:247], off
	global_load_ushort v117, v[246:247], off offset:64
	global_load_ushort v118, v[246:247], off offset:128
	global_load_ushort v119, v[246:247], off offset:192
	v_mad_i64_i32 v[240:241], s[38:39], v229, s40, 0
	v_or_b32_e32 v240, v240, v214
	v_lshlrev_b64 v[240:241], 1, v[240:241]
	v_lshl_add_u64 v[192:193], s[46:47], 0, v[240:241]
	v_lshl_add_u64 v[246:247], s[44:45], 0, v[240:241]
	v_lshl_add_u64 v[240:241], s[42:43], 0, v[240:241]
	global_load_ushort v120, v[192:193], off
	global_load_ushort v121, v[192:193], off offset:64
	global_load_ushort v122, v[192:193], off offset:128
	global_load_ushort v123, v[192:193], off offset:192
	global_load_ushort v124, v[246:247], off
	global_load_ushort v125, v[246:247], off offset:64
	global_load_ushort v126, v[246:247], off offset:128
	global_load_ushort v127, v[246:247], off offset:192
	v_mad_i64_i32 v[242:243], s[38:39], v233, s40, 0
	v_or_b32_e32 v242, v242, v214
	v_lshlrev_b64 v[242:243], 1, v[242:243]
	v_lshl_add_u64 v[192:193], s[46:47], 0, v[242:243]
	v_lshl_add_u64 v[246:247], s[44:45], 0, v[242:243]
	v_lshl_add_u64 v[242:243], s[42:43], 0, v[242:243]
	global_load_ushort v84, v[192:193], off
	global_load_ushort v85, v[192:193], off offset:64
	global_load_ushort v86, v[192:193], off offset:128
	global_load_ushort v87, v[192:193], off offset:192
	global_load_ushort v88, v[246:247], off
	global_load_ushort v89, v[246:247], off offset:64
	global_load_ushort v90, v[246:247], off offset:128
	global_load_ushort v91, v[246:247], off offset:192
	v_mad_i64_i32 v[244:245], s[38:39], v237, s40, 0
	v_or_b32_e32 v244, v244, v214
	v_lshlrev_b64 v[244:245], 1, v[244:245]
	v_lshl_add_u64 v[192:193], s[46:47], 0, v[244:245]
	v_lshl_add_u64 v[246:247], s[44:45], 0, v[244:245]
	v_lshl_add_u64 v[244:245], s[42:43], 0, v[244:245]
	global_load_ushort v92, v[192:193], off
	global_load_ushort v93, v[192:193], off offset:64
	global_load_ushort v94, v[192:193], off offset:128
	global_load_ushort v95, v[192:193], off offset:192
	global_load_ushort v96, v[246:247], off
	global_load_ushort v97, v[246:247], off offset:64
	global_load_ushort v98, v[246:247], off offset:128
	global_load_ushort v99, v[246:247], off offset:192
	s_waitcnt vmcnt(32)
; __device__ __forceinline__ unsigned cvt_pk_bf16(float lo, float hi) { unsigned r; asm volatile("v_cvt_pk_bf16_f32 %0, %1, %2" : "=v"(r) : "v"(lo), "v"(hi)); return r; }
; __device__ __forceinline__ float bf2f(unsigned short h) { return __uint_as_float(((unsigned)h) << 16); }
; __device__ __forceinline__ int crow(int r, int hi) { return (r & 3) + 8 * (r >> 2) + 4 * hi; }
; template <int MODE>
; __device__ __forceinline__ void body(const Desc& d, char* lds, int wave_id) {
;     ...
; #pragma unroll
;   for (int r = 0; r < 16; ++r) { const int rr = crow(r, hi); const float ww = li_l[rr]; const size_t ob = (size_t)tk_l[rr] * d.ldo + r32;
;     float a1 = 0.f, a2 = 0.f; if (MODE == 0 && d.comb) { a1 = al_l[rr]; a2 = w2_l[rr]; }
; #pragma unroll
;     for (int d0 = 0; d0 < 4; ++d0) { float v = o[d0][r] * ww;
;       if (MODE == 0 && d.comb) v += a1 * bf2f(d.O1[ob + d0 * 32]) + a2 * bf2f(d.O2[ob + d0 * 32]);
;       d.O[ob + d0 * 32] = (bf16_t)(cvt_pk_bf16(v, v) & 0xffff); } }
	v_lshlrev_b32_e32 v144, 16, v144
	v_lshlrev_b32_e32 v145, 16, v145
	v_lshlrev_b32_e32 v146, 16, v146
	v_lshlrev_b32_e32 v147, 16, v147
	v_lshlrev_b32_e32 v148, 16, v148
	v_lshlrev_b32_e32 v149, 16, v149
	v_lshlrev_b32_e32 v150, 16, v150
	v_lshlrev_b32_e32 v151, 16, v151
	v_mul_f32_e32 v148, v178, v148
	v_mul_f32_e32 v149, v178, v149
	v_mul_f32_e32 v150, v178, v150
	v_mul_f32_e32 v151, v178, v151
	v_fmac_f32_e32 v148, v177, v144
	v_fmac_f32_e32 v149, v177, v145
	v_fmac_f32_e32 v150, v177, v146
	v_fmac_f32_e32 v151, v177, v147
	v_fmac_f32_e32 v148, v48, v176
	v_fmac_f32_e32 v149, v32, v176
	v_fmac_f32_e32 v150, v16, v176
	v_fmac_f32_e32 v151, v0, v176
	v_cvt_pk_bf16_f32 v148, v148, v148
	v_cvt_pk_bf16_f32 v149, v149, v149
	v_cvt_pk_bf16_f32 v150, v150, v150
	v_cvt_pk_bf16_f32 v151, v151, v151
	global_store_short v[76:77], v148, off
	global_store_short v[76:77], v149, off offset:64
	global_store_short v[76:77], v150, off offset:128
	global_store_short v[76:77], v151, off offset:192
	v_lshlrev_b32_e32 v152, 16, v152
	v_lshlrev_b32_e32 v153, 16, v153
	v_lshlrev_b32_e32 v154, 16, v154
	v_lshlrev_b32_e32 v155, 16, v155
	v_lshlrev_b32_e32 v156, 16, v156
	v_lshlrev_b32_e32 v157, 16, v157
	v_lshlrev_b32_e32 v158, 16, v158
	v_lshlrev_b32_e32 v159, 16, v159
	v_mul_f32_e32 v156, v182, v156
	v_mul_f32_e32 v157, v182, v157
	v_mul_f32_e32 v158, v182, v158
	v_mul_f32_e32 v159, v182, v159
	v_fmac_f32_e32 v156, v181, v152
	v_fmac_f32_e32 v157, v181, v153
	v_fmac_f32_e32 v158, v181, v154
	v_fmac_f32_e32 v159, v181, v155
	v_fmac_f32_e32 v156, v49, v180
	v_fmac_f32_e32 v157, v33, v180
	v_fmac_f32_e32 v158, v17, v180
	v_fmac_f32_e32 v159, v1, v180
	v_cvt_pk_bf16_f32 v156, v156, v156
	v_cvt_pk_bf16_f32 v157, v157, v157
	v_cvt_pk_bf16_f32 v158, v158, v158
	v_cvt_pk_bf16_f32 v159, v159, v159
	global_store_short v[78:79], v156, off
	global_store_short v[78:79], v157, off offset:64
	global_store_short v[78:79], v158, off offset:128
	global_store_short v[78:79], v159, off offset:192
	v_lshlrev_b32_e32 v160, 16, v160
	v_lshlrev_b32_e32 v161, 16, v161
	v_lshlrev_b32_e32 v162, 16, v162
	v_lshlrev_b32_e32 v163, 16, v163
	v_lshlrev_b32_e32 v164, 16, v164
	v_lshlrev_b32_e32 v165, 16, v165
	v_lshlrev_b32_e32 v166, 16, v166
	v_lshlrev_b32_e32 v167, 16, v167
	v_mul_f32_e32 v164, v186, v164
	v_mul_f32_e32 v165, v186, v165
	v_mul_f32_e32 v166, v186, v166
	v_mul_f32_e32 v167, v186, v167
	v_fmac_f32_e32 v164, v185, v160
	v_fmac_f32_e32 v165, v185, v161
	v_fmac_f32_e32 v166, v185, v162
	v_fmac_f32_e32 v167, v185, v163
	v_fmac_f32_e32 v164, v50, v184
	v_fmac_f32_e32 v165, v34, v184
	v_fmac_f32_e32 v166, v18, v184
	v_fmac_f32_e32 v167, v2, v184
	v_cvt_pk_bf16_f32 v164, v164, v164
	v_cvt_pk_bf16_f32 v165, v165, v165
	v_cvt_pk_bf16_f32 v166, v166, v166
	v_cvt_pk_bf16_f32 v167, v167, v167
	global_store_short v[80:81], v164, off
	global_store_short v[80:81], v165, off offset:64
	global_store_short v[80:81], v166, off offset:128
	global_store_short v[80:81], v167, off offset:192
	v_lshlrev_b32_e32 v168, 16, v168
	v_lshlrev_b32_e32 v169, 16, v169
	v_lshlrev_b32_e32 v170, 16, v170
	v_lshlrev_b32_e32 v171, 16, v171
	v_lshlrev_b32_e32 v172, 16, v172
	v_lshlrev_b32_e32 v173, 16, v173
	v_lshlrev_b32_e32 v174, 16, v174
	v_lshlrev_b32_e32 v175, 16, v175
	v_mul_f32_e32 v172, v190, v172
	v_mul_f32_e32 v173, v190, v173
	v_mul_f32_e32 v174, v190, v174
	v_mul_f32_e32 v175, v190, v175
	v_fmac_f32_e32 v172, v189, v168
	v_fmac_f32_e32 v173, v189, v169
	v_fmac_f32_e32 v174, v189, v170
	v_fmac_f32_e32 v175, v189, v171
	v_fmac_f32_e32 v172, v51, v188
	v_fmac_f32_e32 v173, v35, v188
	v_fmac_f32_e32 v174, v19, v188
	v_fmac_f32_e32 v175, v3, v188
	v_cvt_pk_bf16_f32 v172, v172, v172
	v_cvt_pk_bf16_f32 v173, v173, v173
	v_cvt_pk_bf16_f32 v174, v174, v174
	v_cvt_pk_bf16_f32 v175, v175, v175
	global_store_short v[82:83], v172, off
	global_store_short v[82:83], v173, off offset:64
	global_store_short v[82:83], v174, off offset:128
	global_store_short v[82:83], v175, off offset:192
	ds_read2_b32 v[176:177], v64 offset0:16 offset1:48
	ds_read2_b32 v[178:179], v64 offset0:80 offset1:112
	ds_read2_b32 v[180:181], v64 offset0:17 offset1:49
	ds_read2_b32 v[182:183], v64 offset0:81 offset1:113
	ds_read2_b32 v[184:185], v64 offset0:18 offset1:50
	ds_read2_b32 v[186:187], v64 offset0:82 offset1:114
	ds_read2_b32 v[188:189], v64 offset0:19 offset1:51
	ds_read2_b32 v[190:191], v64 offset0:83 offset1:115
	s_waitcnt lgkmcnt(0)
; __device__ __forceinline__ unsigned cvt_pk_bf16(float lo, float hi) { unsigned r; asm volatile("v_cvt_pk_bf16_f32 %0, %1, %2" : "=v"(r) : "v"(lo), "v"(hi)); return r; }
; __device__ __forceinline__ float bf2f(unsigned short h) { return __uint_as_float(((unsigned)h) << 16); }
; __device__ __forceinline__ int crow(int r, int hi) { return (r & 3) + 8 * (r >> 2) + 4 * hi; }
; template <int MODE>
; __device__ __forceinline__ void body(const Desc& d, char* lds, int wave_id) {
;     ...
;   for (int r = 0; r < 16; ++r) { const int rr = crow(r, hi); const float ww = li_l[rr]; const size_t ob = (size_t)tk_l[rr] * d.ldo + r32;
;     float a1 = 0.f, a2 = 0.f; if (MODE == 0 && d.comb) { a1 = al_l[rr]; a2 = w2_l[rr]; }
; #pragma unroll
;     for (int d0 = 0; d0 < 4; ++d0) { float v = o[d0][r] * ww;
;       if (MODE == 0 && d.comb) v += a1 * bf2f(d.O1[ob + d0 * 32]) + a2 * bf2f(d.O2[ob + d0 * 32]);
;       d.O[ob + d0 * 32] = (bf16_t)(cvt_pk_bf16(v, v) & 0xffff); } }
	v_mad_i64_i32 v[76:77], s[38:39], v179, s40, 0
	v_or_b32_e32 v76, v76, v214
	v_lshlrev_b64 v[76:77], 1, v[76:77]
	v_lshl_add_u64 v[192:193], s[46:47], 0, v[76:77]
	v_lshl_add_u64 v[246:247], s[44:45], 0, v[76:77]
	v_lshl_add_u64 v[76:77], s[42:43], 0, v[76:77]
	global_load_ushort v144, v[192:193], off
	global_load_ushort v145, v[192:193], off offset:64
	global_load_ushort v146, v[192:193], off offset:128
	global_load_ushort v147, v[192:193], off offset:192
	global_load_ushort v148, v[246:247], off
	global_load_ushort v149, v[246:247], off offset:64
	global_load_ushort v150, v[246:247], off offset:128
	global_load_ushort v151, v[246:247], off offset:192
	v_mad_i64_i32 v[78:79], s[38:39], v183, s40, 0
	v_or_b32_e32 v78, v78, v214
	v_lshlrev_b64 v[78:79], 1, v[78:79]
	v_lshl_add_u64 v[192:193], s[46:47], 0, v[78:79]
	v_lshl_add_u64 v[246:247], s[44:45], 0, v[78:79]
	v_lshl_add_u64 v[78:79], s[42:43], 0, v[78:79]
	global_load_ushort v152, v[192:193], off
	global_load_ushort v153, v[192:193], off offset:64
	global_load_ushort v154, v[192:193], off offset:128
	global_load_ushort v155, v[192:193], off offset:192
	global_load_ushort v156, v[246:247], off
	global_load_ushort v157, v[246:247], off offset:64
	global_load_ushort v158, v[246:247], off offset:128
	global_load_ushort v159, v[246:247], off offset:192
	v_mad_i64_i32 v[80:81], s[38:39], v187, s40, 0
	v_or_b32_e32 v80, v80, v214
	v_lshlrev_b64 v[80:81], 1, v[80:81]
	v_lshl_add_u64 v[192:193], s[46:47], 0, v[80:81]
	v_lshl_add_u64 v[246:247], s[44:45], 0, v[80:81]
	v_lshl_add_u64 v[80:81], s[42:43], 0, v[80:81]
	global_load_ushort v160, v[192:193], off
	global_load_ushort v161, v[192:193], off offset:64
	global_load_ushort v162, v[192:193], off offset:128
	global_load_ushort v163, v[192:193], off offset:192
	global_load_ushort v164, v[246:247], off
	global_load_ushort v165, v[246:247], off offset:64
	global_load_ushort v166, v[246:247], off offset:128
	global_load_ushort v167, v[246:247], off offset:192
	v_mad_i64_i32 v[82:83], s[38:39], v191, s40, 0
	v_or_b32_e32 v82, v82, v214
	v_lshlrev_b64 v[82:83], 1, v[82:83]
	v_lshl_add_u64 v[192:193], s[46:47], 0, v[82:83]
	v_lshl_add_u64 v[246:247], s[44:45], 0, v[82:83]
	v_lshl_add_u64 v[82:83], s[42:43], 0, v[82:83]
	global_load_ushort v168, v[192:193], off
	global_load_ushort v169, v[192:193], off offset:64
	global_load_ushort v170, v[192:193], off offset:128
	global_load_ushort v171, v[192:193], off offset:192
	global_load_ushort v172, v[246:247], off
	global_load_ushort v173, v[246:247], off offset:64
	global_load_ushort v174, v[246:247], off offset:128
	global_load_ushort v175, v[246:247], off offset:192
	s_waitcnt vmcnt(32)
	v_lshlrev_b32_e32 v112, 16, v112
	v_lshlrev_b32_e32 v113, 16, v113
	v_lshlrev_b32_e32 v114, 16, v114
	v_lshlrev_b32_e32 v115, 16, v115
	v_lshlrev_b32_e32 v116, 16, v116
	v_lshlrev_b32_e32 v117, 16, v117
	v_lshlrev_b32_e32 v118, 16, v118
	v_lshlrev_b32_e32 v119, 16, v119
	v_mul_f32_e32 v116, v224, v116
	v_mul_f32_e32 v117, v224, v117
	v_mul_f32_e32 v118, v224, v118
	v_mul_f32_e32 v119, v224, v119
	v_fmac_f32_e32 v116, v223, v112
	v_fmac_f32_e32 v117, v223, v113
	v_fmac_f32_e32 v118, v223, v114
	v_fmac_f32_e32 v119, v223, v115
	v_fmac_f32_e32 v116, v52, v222
	v_fmac_f32_e32 v117, v36, v222
	v_fmac_f32_e32 v118, v20, v222
	v_fmac_f32_e32 v119, v4, v222
	v_cvt_pk_bf16_f32 v116, v116, v116
	v_cvt_pk_bf16_f32 v117, v117, v117
	v_cvt_pk_bf16_f32 v118, v118, v118
	v_cvt_pk_bf16_f32 v119, v119, v119
	global_store_short v[238:239], v116, off
	global_store_short v[238:239], v117, off offset:64
	global_store_short v[238:239], v118, off offset:128
	global_store_short v[238:239], v119, off offset:192
	v_lshlrev_b32_e32 v120, 16, v120
	v_lshlrev_b32_e32 v121, 16, v121
	v_lshlrev_b32_e32 v122, 16, v122
	v_lshlrev_b32_e32 v123, 16, v123
	v_lshlrev_b32_e32 v124, 16, v124
	v_lshlrev_b32_e32 v125, 16, v125
	v_lshlrev_b32_e32 v126, 16, v126
	v_lshlrev_b32_e32 v127, 16, v127
	v_mul_f32_e32 v124, v228, v124
	v_mul_f32_e32 v125, v228, v125
	v_mul_f32_e32 v126, v228, v126
	v_mul_f32_e32 v127, v228, v127
	v_fmac_f32_e32 v124, v227, v120
	v_fmac_f32_e32 v125, v227, v121
	v_fmac_f32_e32 v126, v227, v122
	v_fmac_f32_e32 v127, v227, v123
	v_fmac_f32_e32 v124, v53, v226
	v_fmac_f32_e32 v125, v37, v226
	v_fmac_f32_e32 v126, v21, v226
	v_fmac_f32_e32 v127, v5, v226
	v_cvt_pk_bf16_f32 v124, v124, v124
	v_cvt_pk_bf16_f32 v125, v125, v125
	v_cvt_pk_bf16_f32 v126, v126, v126
	v_cvt_pk_bf16_f32 v127, v127, v127
	global_store_short v[240:241], v124, off
	global_store_short v[240:241], v125, off offset:64
	global_store_short v[240:241], v126, off offset:128
	global_store_short v[240:241], v127, off offset:192
	v_lshlrev_b32_e32 v84, 16, v84
	v_lshlrev_b32_e32 v85, 16, v85
	v_lshlrev_b32_e32 v86, 16, v86
	v_lshlrev_b32_e32 v87, 16, v87
	v_lshlrev_b32_e32 v88, 16, v88
	v_lshlrev_b32_e32 v89, 16, v89
	v_lshlrev_b32_e32 v90, 16, v90
	v_lshlrev_b32_e32 v91, 16, v91
	v_mul_f32_e32 v88, v232, v88
	v_mul_f32_e32 v89, v232, v89
	v_mul_f32_e32 v90, v232, v90
	v_mul_f32_e32 v91, v232, v91
	v_fmac_f32_e32 v88, v231, v84
	v_fmac_f32_e32 v89, v231, v85
	v_fmac_f32_e32 v90, v231, v86
	v_fmac_f32_e32 v91, v231, v87
	v_fmac_f32_e32 v88, v54, v230
	v_fmac_f32_e32 v89, v38, v230
	v_fmac_f32_e32 v90, v22, v230
	v_fmac_f32_e32 v91, v6, v230
	v_cvt_pk_bf16_f32 v88, v88, v88
	v_cvt_pk_bf16_f32 v89, v89, v89
	v_cvt_pk_bf16_f32 v90, v90, v90
	v_cvt_pk_bf16_f32 v91, v91, v91
	global_store_short v[242:243], v88, off
	global_store_short v[242:243], v89, off offset:64
	global_store_short v[242:243], v90, off offset:128
	global_store_short v[242:243], v91, off offset:192
	v_lshlrev_b32_e32 v92, 16, v92
	v_lshlrev_b32_e32 v93, 16, v93
	v_lshlrev_b32_e32 v94, 16, v94
	v_lshlrev_b32_e32 v95, 16, v95
	v_lshlrev_b32_e32 v96, 16, v96
	v_lshlrev_b32_e32 v97, 16, v97
	v_lshlrev_b32_e32 v98, 16, v98
	v_lshlrev_b32_e32 v99, 16, v99
	v_mul_f32_e32 v96, v236, v96
	v_mul_f32_e32 v97, v236, v97
	v_mul_f32_e32 v98, v236, v98
	v_mul_f32_e32 v99, v236, v99
	v_fmac_f32_e32 v96, v235, v92
	v_fmac_f32_e32 v97, v235, v93
	v_fmac_f32_e32 v98, v235, v94
	v_fmac_f32_e32 v99, v235, v95
	v_fmac_f32_e32 v96, v55, v234
	v_fmac_f32_e32 v97, v39, v234
	v_fmac_f32_e32 v98, v23, v234
	v_fmac_f32_e32 v99, v7, v234
	v_cvt_pk_bf16_f32 v96, v96, v96
	v_cvt_pk_bf16_f32 v97, v97, v97
	v_cvt_pk_bf16_f32 v98, v98, v98
	v_cvt_pk_bf16_f32 v99, v99, v99
	global_store_short v[244:245], v96, off
	global_store_short v[244:245], v97, off offset:64
	global_store_short v[244:245], v98, off offset:128
	global_store_short v[244:245], v99, off offset:192
	ds_read2_b32 v[222:223], v64 offset0:24 offset1:56
	ds_read2_b32 v[224:225], v64 offset0:88 offset1:120
	ds_read2_b32 v[226:227], v64 offset0:25 offset1:57
	ds_read2_b32 v[228:229], v64 offset0:89 offset1:121
	ds_read2_b32 v[230:231], v64 offset0:26 offset1:58
	ds_read2_b32 v[232:233], v64 offset0:90 offset1:122
	ds_read2_b32 v[234:235], v64 offset0:27 offset1:59
	ds_read2_b32 v[236:237], v64 offset0:91 offset1:123
	s_waitcnt lgkmcnt(0)
; __device__ __forceinline__ unsigned cvt_pk_bf16(float lo, float hi) { unsigned r; asm volatile("v_cvt_pk_bf16_f32 %0, %1, %2" : "=v"(r) : "v"(lo), "v"(hi)); return r; }
; __device__ __forceinline__ float bf2f(unsigned short h) { return __uint_as_float(((unsigned)h) << 16); }
; __device__ __forceinline__ int crow(int r, int hi) { return (r & 3) + 8 * (r >> 2) + 4 * hi; }
; template <int MODE>
; __device__ __forceinline__ void body(const Desc& d, char* lds, int wave_id) {
;     ...
;   for (int r = 0; r < 16; ++r) { const int rr = crow(r, hi); const float ww = li_l[rr]; const size_t ob = (size_t)tk_l[rr] * d.ldo + r32;
;     float a1 = 0.f, a2 = 0.f; if (MODE == 0 && d.comb) { a1 = al_l[rr]; a2 = w2_l[rr]; }
; #pragma unroll
;     for (int d0 = 0; d0 < 4; ++d0) { float v = o[d0][r] * ww;
;       if (MODE == 0 && d.comb) v += a1 * bf2f(d.O1[ob + d0 * 32]) + a2 * bf2f(d.O2[ob + d0 * 32]);
;       d.O[ob + d0 * 32] = (bf16_t)(cvt_pk_bf16(v, v) & 0xffff); } }
	v_mad_i64_i32 v[238:239], s[38:39], v225, s40, 0
	v_or_b32_e32 v238, v238, v214
	v_lshlrev_b64 v[238:239], 1, v[238:239]
	v_lshl_add_u64 v[192:193], s[46:47], 0, v[238:239]
	v_lshl_add_u64 v[246:247], s[44:45], 0, v[238:239]
	v_lshl_add_u64 v[238:239], s[42:43], 0, v[238:239]
	global_load_ushort v112, v[192:193], off
	global_load_ushort v113, v[192:193], off offset:64
	global_load_ushort v114, v[192:193], off offset:128
	global_load_ushort v115, v[192:193], off offset:192
	global_load_ushort v116, v[246:247], off
	global_load_ushort v117, v[246:247], off offset:64
	global_load_ushort v118, v[246:247], off offset:128
	global_load_ushort v119, v[246:247], off offset:192
	v_mad_i64_i32 v[240:241], s[38:39], v229, s40, 0
	v_or_b32_e32 v240, v240, v214
	v_lshlrev_b64 v[240:241], 1, v[240:241]
	v_lshl_add_u64 v[192:193], s[46:47], 0, v[240:241]
	v_lshl_add_u64 v[246:247], s[44:45], 0, v[240:241]
	v_lshl_add_u64 v[240:241], s[42:43], 0, v[240:241]
	global_load_ushort v120, v[192:193], off
	global_load_ushort v121, v[192:193], off offset:64
	global_load_ushort v122, v[192:193], off offset:128
	global_load_ushort v123, v[192:193], off offset:192
	global_load_ushort v124, v[246:247], off
	global_load_ushort v125, v[246:247], off offset:64
	global_load_ushort v126, v[246:247], off offset:128
	global_load_ushort v127, v[246:247], off offset:192
	v_mad_i64_i32 v[242:243], s[38:39], v233, s40, 0
	v_or_b32_e32 v242, v242, v214
	v_lshlrev_b64 v[242:243], 1, v[242:243]
	v_lshl_add_u64 v[192:193], s[46:47], 0, v[242:243]
	v_lshl_add_u64 v[246:247], s[44:45], 0, v[242:243]
	v_lshl_add_u64 v[242:243], s[42:43], 0, v[242:243]
	global_load_ushort v84, v[192:193], off
	global_load_ushort v85, v[192:193], off offset:64
	global_load_ushort v86, v[192:193], off offset:128
	global_load_ushort v87, v[192:193], off offset:192
	global_load_ushort v88, v[246:247], off
	global_load_ushort v89, v[246:247], off offset:64
	global_load_ushort v90, v[246:247], off offset:128
	global_load_ushort v91, v[246:247], off offset:192
	v_mad_i64_i32 v[244:245], s[38:39], v237, s40, 0
	v_or_b32_e32 v244, v244, v214
	v_lshlrev_b64 v[244:245], 1, v[244:245]
	v_lshl_add_u64 v[192:193], s[46:47], 0, v[244:245]
	v_lshl_add_u64 v[246:247], s[44:45], 0, v[244:245]
	v_lshl_add_u64 v[244:245], s[42:43], 0, v[244:245]
	global_load_ushort v92, v[192:193], off
	global_load_ushort v93, v[192:193], off offset:64
	global_load_ushort v94, v[192:193], off offset:128
	global_load_ushort v95, v[192:193], off offset:192
	global_load_ushort v96, v[246:247], off
	global_load_ushort v97, v[246:247], off offset:64
	global_load_ushort v98, v[246:247], off offset:128
	global_load_ushort v99, v[246:247], off offset:192
	s_waitcnt vmcnt(32)
	v_lshlrev_b32_e32 v144, 16, v144
	v_lshlrev_b32_e32 v145, 16, v145
	v_lshlrev_b32_e32 v146, 16, v146
	v_lshlrev_b32_e32 v147, 16, v147
	v_lshlrev_b32_e32 v148, 16, v148
	v_lshlrev_b32_e32 v149, 16, v149
	v_lshlrev_b32_e32 v150, 16, v150
	v_lshlrev_b32_e32 v151, 16, v151
	v_mul_f32_e32 v148, v178, v148
	v_mul_f32_e32 v149, v178, v149
	v_mul_f32_e32 v150, v178, v150
	v_mul_f32_e32 v151, v178, v151
	v_fmac_f32_e32 v148, v177, v144
	v_fmac_f32_e32 v149, v177, v145
	v_fmac_f32_e32 v150, v177, v146
	v_fmac_f32_e32 v151, v177, v147
	v_fmac_f32_e32 v148, v56, v176
	v_fmac_f32_e32 v149, v40, v176
	v_fmac_f32_e32 v150, v24, v176
	v_fmac_f32_e32 v151, v8, v176
	v_cvt_pk_bf16_f32 v148, v148, v148
	v_cvt_pk_bf16_f32 v149, v149, v149
	v_cvt_pk_bf16_f32 v150, v150, v150
	v_cvt_pk_bf16_f32 v151, v151, v151
	global_store_short v[76:77], v148, off
	global_store_short v[76:77], v149, off offset:64
	global_store_short v[76:77], v150, off offset:128
	global_store_short v[76:77], v151, off offset:192
	v_lshlrev_b32_e32 v152, 16, v152
	v_lshlrev_b32_e32 v153, 16, v153
	v_lshlrev_b32_e32 v154, 16, v154
	v_lshlrev_b32_e32 v155, 16, v155
	v_lshlrev_b32_e32 v156, 16, v156
	v_lshlrev_b32_e32 v157, 16, v157
	v_lshlrev_b32_e32 v158, 16, v158
	v_lshlrev_b32_e32 v159, 16, v159
	v_mul_f32_e32 v156, v182, v156
	v_mul_f32_e32 v157, v182, v157
	v_mul_f32_e32 v158, v182, v158
	v_mul_f32_e32 v159, v182, v159
	v_fmac_f32_e32 v156, v181, v152
	v_fmac_f32_e32 v157, v181, v153
	v_fmac_f32_e32 v158, v181, v154
	v_fmac_f32_e32 v159, v181, v155
	v_fmac_f32_e32 v156, v57, v180
	v_fmac_f32_e32 v157, v41, v180
	v_fmac_f32_e32 v158, v25, v180
	v_fmac_f32_e32 v159, v9, v180
	v_cvt_pk_bf16_f32 v156, v156, v156
	v_cvt_pk_bf16_f32 v157, v157, v157
	v_cvt_pk_bf16_f32 v158, v158, v158
	v_cvt_pk_bf16_f32 v159, v159, v159
	global_store_short v[78:79], v156, off
	global_store_short v[78:79], v157, off offset:64
	global_store_short v[78:79], v158, off offset:128
	global_store_short v[78:79], v159, off offset:192
	v_lshlrev_b32_e32 v160, 16, v160
	v_lshlrev_b32_e32 v161, 16, v161
	v_lshlrev_b32_e32 v162, 16, v162
	v_lshlrev_b32_e32 v163, 16, v163
	v_lshlrev_b32_e32 v164, 16, v164
	v_lshlrev_b32_e32 v165, 16, v165
	v_lshlrev_b32_e32 v166, 16, v166
	v_lshlrev_b32_e32 v167, 16, v167
	v_mul_f32_e32 v164, v186, v164
	v_mul_f32_e32 v165, v186, v165
	v_mul_f32_e32 v166, v186, v166
	v_mul_f32_e32 v167, v186, v167
	v_fmac_f32_e32 v164, v185, v160
	v_fmac_f32_e32 v165, v185, v161
	v_fmac_f32_e32 v166, v185, v162
	v_fmac_f32_e32 v167, v185, v163
	v_fmac_f32_e32 v164, v58, v184
	v_fmac_f32_e32 v165, v42, v184
	v_fmac_f32_e32 v166, v26, v184
	v_fmac_f32_e32 v167, v10, v184
	v_cvt_pk_bf16_f32 v164, v164, v164
	v_cvt_pk_bf16_f32 v165, v165, v165
	v_cvt_pk_bf16_f32 v166, v166, v166
	v_cvt_pk_bf16_f32 v167, v167, v167
	global_store_short v[80:81], v164, off
	global_store_short v[80:81], v165, off offset:64
	global_store_short v[80:81], v166, off offset:128
	global_store_short v[80:81], v167, off offset:192
	v_lshlrev_b32_e32 v168, 16, v168
	v_lshlrev_b32_e32 v169, 16, v169
	v_lshlrev_b32_e32 v170, 16, v170
	v_lshlrev_b32_e32 v171, 16, v171
	v_lshlrev_b32_e32 v172, 16, v172
	v_lshlrev_b32_e32 v173, 16, v173
	v_lshlrev_b32_e32 v174, 16, v174
	v_lshlrev_b32_e32 v175, 16, v175
	v_mul_f32_e32 v172, v190, v172
	v_mul_f32_e32 v173, v190, v173
	v_mul_f32_e32 v174, v190, v174
	v_mul_f32_e32 v175, v190, v175
	v_fmac_f32_e32 v172, v189, v168
	v_fmac_f32_e32 v173, v189, v169
	v_fmac_f32_e32 v174, v189, v170
	v_fmac_f32_e32 v175, v189, v171
	v_fmac_f32_e32 v172, v59, v188
	v_fmac_f32_e32 v173, v43, v188
	v_fmac_f32_e32 v174, v27, v188
	v_fmac_f32_e32 v175, v11, v188
	v_cvt_pk_bf16_f32 v172, v172, v172
	v_cvt_pk_bf16_f32 v173, v173, v173
	v_cvt_pk_bf16_f32 v174, v174, v174
	v_cvt_pk_bf16_f32 v175, v175, v175
	global_store_short v[82:83], v172, off
	global_store_short v[82:83], v173, off offset:64
	global_store_short v[82:83], v174, off offset:128
	global_store_short v[82:83], v175, off offset:192
	s_waitcnt vmcnt(0)
; __device__ __forceinline__ unsigned cvt_pk_bf16(float lo, float hi) { unsigned r; asm volatile("v_cvt_pk_bf16_f32 %0, %1, %2" : "=v"(r) : "v"(lo), "v"(hi)); return r; }
; __device__ __forceinline__ float bf2f(unsigned short h) { return __uint_as_float(((unsigned)h) << 16); }
; __device__ __forceinline__ int crow(int r, int hi) { return (r & 3) + 8 * (r >> 2) + 4 * hi; }
; template <int MODE>
; __device__ __forceinline__ void body(const Desc& d, char* lds, int wave_id) {
;     ...
;   for (int r = 0; r < 16; ++r) { const int rr = crow(r, hi); const float ww = li_l[rr]; const size_t ob = (size_t)tk_l[rr] * d.ldo + r32;
;     float a1 = 0.f, a2 = 0.f; if (MODE == 0 && d.comb) { a1 = al_l[rr]; a2 = w2_l[rr]; }
; #pragma unroll
;     for (int d0 = 0; d0 < 4; ++d0) { float v = o[d0][r] * ww;
;       if (MODE == 0 && d.comb) v += a1 * bf2f(d.O1[ob + d0 * 32]) + a2 * bf2f(d.O2[ob + d0 * 32]);
;       d.O[ob + d0 * 32] = (bf16_t)(cvt_pk_bf16(v, v) & 0xffff); } }
; __global__ void __launch_bounds__(512) mega_fwd(Params P) {
;     ...
;             for (int i = bx; i < 960; i += G) {
	v_lshlrev_b32_e32 v112, 16, v112
	v_lshlrev_b32_e32 v113, 16, v113
	v_lshlrev_b32_e32 v114, 16, v114
	v_lshlrev_b32_e32 v115, 16, v115
	v_lshlrev_b32_e32 v116, 16, v116
	v_lshlrev_b32_e32 v117, 16, v117
	v_lshlrev_b32_e32 v118, 16, v118
	v_lshlrev_b32_e32 v119, 16, v119
	v_mul_f32_e32 v116, v224, v116
	v_mul_f32_e32 v117, v224, v117
	v_mul_f32_e32 v118, v224, v118
	v_mul_f32_e32 v119, v224, v119
	v_fmac_f32_e32 v116, v223, v112
	v_fmac_f32_e32 v117, v223, v113
	v_fmac_f32_e32 v118, v223, v114
	v_fmac_f32_e32 v119, v223, v115
	v_fmac_f32_e32 v116, v60, v222
	v_fmac_f32_e32 v117, v44, v222
	v_fmac_f32_e32 v118, v28, v222
	v_fmac_f32_e32 v119, v12, v222
	v_cvt_pk_bf16_f32 v116, v116, v116
	v_cvt_pk_bf16_f32 v117, v117, v117
	v_cvt_pk_bf16_f32 v118, v118, v118
	v_cvt_pk_bf16_f32 v119, v119, v119
	global_store_short v[238:239], v116, off
	global_store_short v[238:239], v117, off offset:64
	global_store_short v[238:239], v118, off offset:128
	global_store_short v[238:239], v119, off offset:192
	v_lshlrev_b32_e32 v120, 16, v120
	v_lshlrev_b32_e32 v121, 16, v121
	v_lshlrev_b32_e32 v122, 16, v122
	v_lshlrev_b32_e32 v123, 16, v123
	v_lshlrev_b32_e32 v124, 16, v124
	v_lshlrev_b32_e32 v125, 16, v125
	v_lshlrev_b32_e32 v126, 16, v126
	v_lshlrev_b32_e32 v127, 16, v127
	v_mul_f32_e32 v124, v228, v124
	v_mul_f32_e32 v125, v228, v125
	v_mul_f32_e32 v126, v228, v126
	v_mul_f32_e32 v127, v228, v127
	v_fmac_f32_e32 v124, v227, v120
	v_fmac_f32_e32 v125, v227, v121
	v_fmac_f32_e32 v126, v227, v122
	v_fmac_f32_e32 v127, v227, v123
	v_fmac_f32_e32 v124, v61, v226
	v_fmac_f32_e32 v125, v45, v226
	v_fmac_f32_e32 v126, v29, v226
	v_fmac_f32_e32 v127, v13, v226
	v_cvt_pk_bf16_f32 v124, v124, v124
	v_cvt_pk_bf16_f32 v125, v125, v125
	v_cvt_pk_bf16_f32 v126, v126, v126
	v_cvt_pk_bf16_f32 v127, v127, v127
	global_store_short v[240:241], v124, off
	global_store_short v[240:241], v125, off offset:64
	global_store_short v[240:241], v126, off offset:128
	global_store_short v[240:241], v127, off offset:192
	v_lshlrev_b32_e32 v84, 16, v84
	v_lshlrev_b32_e32 v85, 16, v85
	v_lshlrev_b32_e32 v86, 16, v86
	v_lshlrev_b32_e32 v87, 16, v87
	v_lshlrev_b32_e32 v88, 16, v88
	v_lshlrev_b32_e32 v89, 16, v89
	v_lshlrev_b32_e32 v90, 16, v90
	v_lshlrev_b32_e32 v91, 16, v91
	v_mul_f32_e32 v88, v232, v88
	v_mul_f32_e32 v89, v232, v89
	v_mul_f32_e32 v90, v232, v90
	v_mul_f32_e32 v91, v232, v91
	v_fmac_f32_e32 v88, v231, v84
	v_fmac_f32_e32 v89, v231, v85
	v_fmac_f32_e32 v90, v231, v86
	v_fmac_f32_e32 v91, v231, v87
	v_fmac_f32_e32 v88, v62, v230
	v_fmac_f32_e32 v89, v46, v230
	v_fmac_f32_e32 v90, v30, v230
	v_fmac_f32_e32 v91, v14, v230
	v_cvt_pk_bf16_f32 v88, v88, v88
	v_cvt_pk_bf16_f32 v89, v89, v89
	v_cvt_pk_bf16_f32 v90, v90, v90
	v_cvt_pk_bf16_f32 v91, v91, v91
	global_store_short v[242:243], v88, off
	global_store_short v[242:243], v89, off offset:64
	global_store_short v[242:243], v90, off offset:128
	global_store_short v[242:243], v91, off offset:192
	v_lshlrev_b32_e32 v92, 16, v92
	v_lshlrev_b32_e32 v93, 16, v93
	v_lshlrev_b32_e32 v94, 16, v94
	v_lshlrev_b32_e32 v95, 16, v95
	v_lshlrev_b32_e32 v96, 16, v96
	v_lshlrev_b32_e32 v97, 16, v97
	v_lshlrev_b32_e32 v98, 16, v98
	v_lshlrev_b32_e32 v99, 16, v99
	v_mul_f32_e32 v96, v236, v96
	v_mul_f32_e32 v97, v236, v97
	v_mul_f32_e32 v98, v236, v98
	v_mul_f32_e32 v99, v236, v99
	v_fmac_f32_e32 v96, v235, v92
	v_fmac_f32_e32 v97, v235, v93
	v_fmac_f32_e32 v98, v235, v94
	v_fmac_f32_e32 v99, v235, v95
	v_fmac_f32_e32 v96, v63, v234
	v_fmac_f32_e32 v97, v47, v234
	v_fmac_f32_e32 v98, v31, v234
	v_fmac_f32_e32 v99, v15, v234
	v_cvt_pk_bf16_f32 v96, v96, v96
	v_cvt_pk_bf16_f32 v97, v97, v97
	v_cvt_pk_bf16_f32 v98, v98, v98
	v_cvt_pk_bf16_f32 v99, v99, v99
	global_store_short v[244:245], v96, off
	global_store_short v[244:245], v97, off offset:64
	global_store_short v[244:245], v98, off offset:128
	global_store_short v[244:245], v99, off offset:192
	s_add_i32 s74, s74, s3
	s_cmpk_lt_i32 s74, 0x3c0
	s_cbranch_scc0 .LBB0_1294
